# v25 plus P7/P10 row phases remapped so a workgroup on XCD x owns rows of batch x (the GEMM phases before and after give batch x to XCD x)
# speedup vs baseline: 1.0021x; 1.0021x over previous
; template <bool FINAL>
; __device__ __forceinline__ void rows_phase(const float* srcL, const float* srcC, int nL, int nTot, const float* g, const float* mod, int sh_off, int sc_off, void* dst, int gw, int NGW, int lane) {
;     asm volatile("" : "+v"(lane));
;     const int per = (nTot + NGW - 1) / NGW; const int r0 = gw * per; int r1 = r0 + per; if (r1 > nTot) r1 = nTot;
;     if (r0 >= r1) return;
;     f32x4 v[8], A[8], B[8]; int cur = -1;
;     { const float* p = (r0 < nL ? srcL + (size_t)r0 * DM : srcC + (size_t)(r0 - nL) * DM) + lane * 4;
; #pragma unroll
;       for (int j = 0; j < 8; ++j) v[j] = *(const f32x4*)(p + j * 256); }
; #pragma unroll 1
;     for (int row = r0; row < r1; ++row) {
;         f32x4 vn[8];
;         const bool more = row + 1 < r1;
;         if (more) { const int rn = row + 1; const float* p = (rn < nL ? srcL + (size_t)rn * DM : srcC + (size_t)(rn - nL) * DM) + lane * 4;
; #pragma unroll
;             for (int j = 0; j < 8; ++j) vn[j] = *(const f32x4*)(p + j * 256); }
.LBB0_1231:
	s_or_b64 exec, exec, s[4:5]
	v_readlane_b32 s5, v242, 42
	s_add_i32 s3, s5, 0x3fff
	s_sub_i32 s5, 0xffffc001, s5
	s_ashr_i32 s4, s3, 31
	s_max_i32 s3, s3, s5
	v_readlane_b32 s5, v242, 28
	v_readlane_b32 s6, v242, 27
	s_mul_hi_u32 s5, s3, s5
	v_readlane_b32 s8, v242, 29
	s_xor_b32 s4, s4, s6
	s_mul_i32 s6, s5, s8
	s_sub_i32 s3, s3, s6
	s_add_i32 s6, s5, 1
	s_sub_i32 s7, s3, s8
	s_cmp_ge_u32 s3, s8
	s_cselect_b32 s5, s6, s5
	s_cselect_b32 s3, s7, s3
	s_add_i32 s6, s5, 1
	s_cmp_ge_u32 s3, s8
	s_cselect_b32 s3, s6, s5
	s_xor_b32 s3, s3, s4
	s_sub_i32 s3, s3, s4
	v_readlane_b32 s4, v242, 43
	s_bfe_u32 s98, s4, 0x30003
	s_lshl_b32 s98, s98, 8
	s_lshr_b32 s99, s4, 6
	s_lshl_b32 s99, s99, 3
	s_add_i32 s98, s98, s99
	s_and_b32 s99, s4, 7
	s_add_i32 s98, s98, s99
	s_cmpk_eq_i32 s30, 0x100
	s_cselect_b32 s4, s98, s4
	s_mul_i32 s8, s3, s4
	s_add_i32 s3, s8, s3
	s_min_i32 s33, s3, 0x4000
	s_cmp_lt_i32 s8, s33
	s_waitcnt lgkmcnt(0)
	v_mov_b32_e32 v0, v177
	s_cselect_b64 s[14:15], -1, 0
	s_cmp_ge_i32 s8, s33
	s_barrier
	s_cbranch_scc1 .LBB0_1238
	s_ashr_i32 s9, s8, 31
	s_lshl_b64 s[4:5], s[8:9], 13
	v_lshlrev_b32_e32 v142, 2, v0
	s_add_u32 s4, s26, s4
	v_ashrrev_i32_e32 v143, 31, v142
	s_addc_u32 s5, s27, s5
	v_lshlrev_b64 v[130:131], 2, v[142:143]
	v_lshl_add_u64 v[140:141], s[4:5], 0, v[130:131]
	global_load_dwordx4 v[60:63], v[140:141], off
	global_load_dwordx4 v[52:55], v[140:141], off offset:1024
	s_movk_i32 s3, 0x1000
	v_add_co_u32_e32 v8, vcc, s3, v140
	v_and_b32_e32 v128, 64, v202
	s_nop 0
	v_addc_co_u32_e32 v9, vcc, 0, v141, vcc
	global_load_dwordx4 v[4:7], v[8:9], off offset:2048
	global_load_dwordx4 v[0:3], v[8:9], off offset:3072
	global_load_dwordx4 v[56:59], v[140:141], off offset:2048
	global_load_dwordx4 v[48:51], v[140:141], off offset:3072
	global_load_dwordx4 v[44:47], v[8:9], off
	global_load_dwordx4 v[40:43], v[8:9], off offset:1024
	v_xor_b32_e32 v129, 1, v202
	v_add_u32_e32 v128, 64, v128
	v_xor_b32_e32 v132, 2, v202
	v_cmp_lt_i32_e32 vcc, v129, v128
	v_xor_b32_e32 v133, 4, v202
	v_xor_b32_e32 v134, 8, v202
	v_cndmask_b32_e32 v129, v202, v129, vcc
	v_cmp_lt_i32_e32 vcc, v132, v128
	v_xor_b32_e32 v135, 16, v202
	v_xor_b32_e32 v136, 32, v202
	v_cndmask_b32_e32 v132, v202, v132, vcc
	v_cmp_lt_i32_e32 vcc, v133, v128
	v_readlane_b32 s40, v242, 0
	v_readlane_b32 s42, v242, 2
	v_cndmask_b32_e32 v133, v202, v133, vcc
	v_cmp_lt_i32_e32 vcc, v134, v128
	v_readlane_b32 s43, v242, 3
	s_mov_b64 s[4:5], 0x1400
	v_cndmask_b32_e32 v134, v202, v134, vcc
	v_cmp_lt_i32_e32 vcc, v135, v128
	v_lshlrev_b32_e32 v147, 2, v129
	s_lshl_b64 s[38:39], s[8:9], 12
	v_cndmask_b32_e32 v135, v202, v135, vcc
	v_cmp_lt_i32_e32 vcc, v136, v128
	v_lshlrev_b32_e32 v150, 2, v134
	v_lshlrev_b32_e32 v151, 2, v135
	v_cndmask_b32_e32 v128, v202, v136, vcc
	v_lshlrev_b32_e32 v152, 2, v128
	v_lshl_add_u64 v[128:129], s[42:43], 0, v[130:131]
	v_lshl_add_u64 v[134:135], v[128:129], 0, s[4:5]
	s_add_u32 s4, s28, s38
	s_addc_u32 s5, s29, s39
	s_mov_b64 s[16:17], 0x1000
	s_mov_b64 s[20:21], 0x1800
	s_mov_b64 s[22:23], 0x1c00
	s_mov_b64 s[36:37], 0x5b00000
	s_mov_b64 s[18:19], 0x2000
	v_lshl_add_u64 v[142:143], v[142:143], 1, s[4:5]
	s_mov_b32 s11, -1
	s_movk_i32 s3, 0x6000
	s_mov_b32 s6, 0x9000
	s_movk_i32 s7, 0x7000
	v_mov_b32_e32 v144, 0x358637bd
	s_mov_b32 s10, 0xf800000
	v_mov_b32_e32 v145, 0x260
	v_mov_b32_e32 v146, 0xc000
	s_mov_b32 s34, s8
	v_lshlrev_b32_e32 v148, 2, v132
	v_lshlrev_b32_e32 v149, 2, v133
	v_lshl_add_u64 v[130:131], s[28:29], 0, v[130:131]
	v_lshl_add_u64 v[132:133], v[128:129], 0, s[16:17]
	v_lshl_add_u64 v[136:137], v[128:129], 0, s[20:21]
	v_lshl_add_u64 v[138:139], v[128:129], 0, s[22:23]
	v_lshl_add_u64 v[140:141], v[140:141], 0, s[18:19]
	v_lshl_add_u64 v[142:143], v[142:143], 0, s[36:37]
	v_readlane_b32 s41, v242, 1
	v_readlane_b32 s44, v242, 4
	v_readlane_b32 s45, v242, 5
	v_readlane_b32 s46, v242, 6
	v_readlane_b32 s47, v242, 7
	s_waitcnt vmcnt(4)
	v_mov_b32_e32 v153, v0
	v_mov_b32_e32 v154, v1
	v_mov_b32_e32 v155, v2
	v_mov_b32_e32 v156, v3
	s_branch .LBB0_1234
